# compress-bias dot-product loop in phase 0: 32 k-steps of loads in flight per trip instead of one load round trip per k (same fmac order)
# speedup vs baseline: 1.0650x; 1.0650x over previous
.LBB0_23:
	global_load_dwordx4 v[24:27], v[12:13], off offset:32
	v_mov_b32_e32 v20, 0
	s_mov_b64 s[6:7], 0
	v_mov_b32_e32 v21, v19
	s_waitcnt vmcnt(0) lgkmcnt(0)
	v_lshl_add_u64 v[14:15], v[26:27], 0, v[8:9]
	v_lshl_add_u64 v[16:17], v[24:25], 0, v[10:11]
	s_mov_b32 s98, 16
	s_mov_b64 s[100:101], 0x1000
.LBB0_24:
	v_lshl_add_u64 v[56:57], v[14:15], 0, s[100:101]
	v_lshl_add_u64 v[58:59], v[56:57], 0, s[100:101]
	v_lshl_add_u64 v[60:61], v[58:59], 0, s[100:101]
	global_load_dword v96, v[14:15], off
	global_load_dword v97, v[14:15], off offset:512
	global_load_dword v98, v[14:15], off offset:1024
	global_load_dword v99, v[14:15], off offset:1536
	global_load_dword v100, v[14:15], off offset:2048
	global_load_dword v101, v[14:15], off offset:2560
	global_load_dword v102, v[14:15], off offset:3072
	global_load_dword v103, v[14:15], off offset:3584
	global_load_dword v104, v[56:57], off
	global_load_dword v105, v[56:57], off offset:512
	global_load_dword v106, v[56:57], off offset:1024
	global_load_dword v107, v[56:57], off offset:1536
	global_load_dword v108, v[56:57], off offset:2048
	global_load_dword v109, v[56:57], off offset:2560
	global_load_dword v110, v[56:57], off offset:3072
	global_load_dword v111, v[56:57], off offset:3584
	global_load_dword v112, v[58:59], off
	global_load_dword v113, v[58:59], off offset:512
	global_load_dword v114, v[58:59], off offset:1024
	global_load_dword v115, v[58:59], off offset:1536
	global_load_dword v116, v[58:59], off offset:2048
	global_load_dword v117, v[58:59], off offset:2560
	global_load_dword v118, v[58:59], off offset:3072
	global_load_dword v119, v[58:59], off offset:3584
	global_load_dword v120, v[60:61], off
	global_load_dword v121, v[60:61], off offset:512
	global_load_dword v122, v[60:61], off offset:1024
	global_load_dword v123, v[60:61], off offset:1536
	global_load_dword v124, v[60:61], off offset:2048
	global_load_dword v125, v[60:61], off offset:2560
	global_load_dword v126, v[60:61], off offset:3072
	global_load_dword v127, v[60:61], off offset:3584
	global_load_dwordx4 v[64:67], v[16:17], off
	global_load_dwordx4 v[68:71], v[16:17], off offset:16
	global_load_dwordx4 v[72:75], v[16:17], off offset:32
	global_load_dwordx4 v[76:79], v[16:17], off offset:48
	global_load_dwordx4 v[80:83], v[16:17], off offset:64
	global_load_dwordx4 v[84:87], v[16:17], off offset:80
	global_load_dwordx4 v[88:91], v[16:17], off offset:96
	global_load_dwordx4 v[92:95], v[16:17], off offset:112
	v_lshl_add_u64 v[14:15], v[60:61], 0, s[100:101]
	v_lshl_add_u64 v[16:17], v[16:17], 0, 64
	v_lshl_add_u64 v[16:17], v[16:17], 0, 64
	s_sub_u32 s98, s98, 1
	s_waitcnt vmcnt(0)
	v_fmac_f32_e32 v20, v64, v96
	v_fmac_f32_e32 v20, v65, v97
	v_fmac_f32_e32 v20, v66, v98
	v_fmac_f32_e32 v20, v67, v99
	v_fmac_f32_e32 v20, v68, v100
	v_fmac_f32_e32 v20, v69, v101
	v_fmac_f32_e32 v20, v70, v102
	v_fmac_f32_e32 v20, v71, v103
	v_fmac_f32_e32 v20, v72, v104
	v_fmac_f32_e32 v20, v73, v105
	v_fmac_f32_e32 v20, v74, v106
	v_fmac_f32_e32 v20, v75, v107
	v_fmac_f32_e32 v20, v76, v108
	v_fmac_f32_e32 v20, v77, v109
	v_fmac_f32_e32 v20, v78, v110
	v_fmac_f32_e32 v20, v79, v111
	v_fmac_f32_e32 v20, v80, v112
	v_fmac_f32_e32 v20, v81, v113
	v_fmac_f32_e32 v20, v82, v114
	v_fmac_f32_e32 v20, v83, v115
	v_fmac_f32_e32 v20, v84, v116
	v_fmac_f32_e32 v20, v85, v117
	v_fmac_f32_e32 v20, v86, v118
	v_fmac_f32_e32 v20, v87, v119
	v_fmac_f32_e32 v20, v88, v120
	v_fmac_f32_e32 v20, v89, v121
	v_fmac_f32_e32 v20, v90, v122
	v_fmac_f32_e32 v20, v91, v123
	v_fmac_f32_e32 v20, v92, v124
	v_fmac_f32_e32 v20, v93, v125
	v_fmac_f32_e32 v20, v94, v126
	v_fmac_f32_e32 v20, v95, v127
	s_cmp_lg_u32 s98, 0
	s_cbranch_scc1 .LBB0_24
	s_or_b64 exec, exec, s[6:7]
	ds_write_b32 v0, v20
	s_waitcnt lgkmcnt(0)
	s_barrier
	s_and_saveexec_b64 s[4:5], vcc
	s_cbranch_execz .LBB0_22
	ds_read2st64_b32 v[14:15], v0 offset1:2
	ds_read2st64_b32 v[16:17], v0 offset0:4 offset1:6
	v_lshl_add_u32 v20, s8, 7, v22
	v_ashrrev_i32_e32 v21, 31, v20
	s_waitcnt lgkmcnt(1)
	v_add_f32_e32 v14, v14, v15
	s_waitcnt lgkmcnt(0)
	v_add_f32_e32 v14, v14, v16
	v_add_f32_e32 v16, v14, v17
	v_lshl_add_u64 v[14:15], v[20:21], 2, v[6:7]
	global_store_dword v[14:15], v16, off
	s_branch .LBB0_22

.LBB0_428:
	s_or_saveexec_b64 s[4:5], s[14:15]
	v_readlane_b32 s6, v255, 10
	v_readlane_b32 s7, v255, 11
	s_lshl_b64 s[8:9], s[6:7], 11
	s_lshl_b64 s[14:15], s[6:7], 15
	s_xor_b64 exec, exec, s[4:5]
	v_cvt_i32_f32_e32 v53, v59
	s_mov_b32 s6, 0xbfc90fda
	v_fma_f32 v54, v59, s6, |v31|
	v_fmac_f32_e32 v54, 0xb3a22168, v59
	v_fmac_f32_e32 v54, 0xa7c234c4, v59
	s_or_b64 exec, exec, s[4:5]
	v_mul_f32_e32 v57, v38, v34
	v_mul_f32_e32 v58, 0x3fb8aa3b, v57
	s_mov_b32 s17, 0x3fb8aa3b
	v_fma_f32 v59, v57, s17, -v58
	v_rndne_f32_e32 v60, v58
	v_fmac_f32_e32 v59, 0x32a5705f, v57
	v_sub_f32_e32 v58, v58, v60
	v_add_f32_e32 v58, v58, v59
	v_exp_f32_e32 v58, v58
	v_cvt_i32_f32_e32 v59, v60
	s_mov_b32 s18, 0xc2ce8ed0
	v_cmp_ngt_f32_e32 vcc, s18, v57
	s_mov_b32 s19, 0x42b17218
	v_ldexp_f32 v58, v58, v59
	v_cndmask_b32_e32 v58, 0, v58, vcc
	v_cmp_nlt_f32_e32 vcc, s19, v57
	v_mov_b32_e32 v64, 0x7f800000
	v_mov_b32_e32 v61, 0x3c0881c4
	v_cndmask_b32_e32 v57, v64, v58, vcc
	v_mul_f32_e32 v58, v56, v56
	v_fmamk_f32 v59, v58, 0xb94c1982, v61
	v_fmaak_f32 v59, v58, v59, 0xbe2aaa9d
	v_mul_f32_e32 v59, v58, v59
	v_mov_b32_e32 v62, 0xbab64f3b
	v_fmac_f32_e32 v56, v56, v59
	v_fmamk_f32 v59, v58, 0x37d75334, v62
	v_fmaak_f32 v59, v58, v59, 0x3d2aabf7
	v_fmaak_f32 v59, v58, v59, 0xbf000004
	v_fma_f32 v58, v58, v59, 1.0
	v_and_b32_e32 v59, 1, v55
	v_cmp_eq_u32_e32 vcc, 0, v59
	v_lshlrev_b32_e32 v55, 30, v55
	s_brev_b32 s11, 1
	v_cndmask_b32_e64 v56, -v56, v58, vcc
	v_bitop3_b32 v55, v55, v56, s11 bitop3:0x6c
	v_mul_f32_e32 v56, v38, v32
	v_mul_f32_e32 v58, 0x3fb8aa3b, v56
	v_fma_f32 v59, v56, s17, -v58
	v_rndne_f32_e32 v60, v58
	v_fmac_f32_e32 v59, 0x32a5705f, v56
	v_sub_f32_e32 v58, v58, v60
	v_add_f32_e32 v58, v58, v59
	v_exp_f32_e32 v58, v58
	v_cvt_i32_f32_e32 v59, v60
	v_cmp_ngt_f32_e32 vcc, s18, v56
	s_movk_i32 s16, 0x1f8
	v_mov_b32_e32 v63, 0x7fc00000
	v_ldexp_f32 v58, v58, v59
	v_cndmask_b32_e32 v58, 0, v58, vcc
	v_cmp_nlt_f32_e32 vcc, s19, v56
	v_cmp_class_f32_e64 s[4:5], v31, s16
	v_mov_b32_e32 v110, 0
	v_cndmask_b32_e32 v56, v64, v58, vcc
	v_mul_f32_e32 v58, v50, v50
	v_fmamk_f32 v59, v58, 0xb94c1982, v61
	v_fmaak_f32 v59, v58, v59, 0xbe2aaa9d
	v_mul_f32_e32 v59, v58, v59
	v_fmac_f32_e32 v50, v50, v59
	v_fmamk_f32 v59, v58, 0x37d75334, v62
	v_fmaak_f32 v59, v58, v59, 0x3d2aabf7
	v_fmaak_f32 v59, v58, v59, 0xbf000004
	v_fma_f32 v58, v58, v59, 1.0
	v_and_b32_e32 v59, 1, v48
	v_cmp_eq_u32_e32 vcc, 0, v59
	v_lshlrev_b32_e32 v48, 30, v48
	v_cndmask_b32_e64 v55, v63, v55, s[4:5]
	v_cndmask_b32_e64 v50, -v50, v58, vcc
	v_bitop3_b32 v48, v48, v50, s11 bitop3:0x6c
	v_mul_f32_e32 v50, v52, v52
	v_fmamk_f32 v58, v50, 0xb94c1982, v61
	v_fmaak_f32 v58, v50, v58, 0xbe2aaa9d
	v_mul_f32_e32 v58, v50, v58
	v_fmac_f32_e32 v52, v52, v58
	v_fmamk_f32 v58, v50, 0x37d75334, v62
	v_fmaak_f32 v58, v50, v58, 0x3d2aabf7
	v_fmaak_f32 v58, v50, v58, 0xbf000004
	v_fma_f32 v50, v50, v58, 1.0
	v_and_b32_e32 v58, 1, v51
	v_lshlrev_b32_e32 v51, 30, v51
	v_cmp_class_f32_e64 vcc, v46, s16
	v_cmp_eq_u32_e64 s[6:7], 0, v58
	v_and_b32_e32 v51, 0x80000000, v51
	v_xor_b32_e32 v46, v47, v46
	v_cndmask_b32_e64 v50, v50, v52, s[6:7]
	v_xor_b32_e32 v46, v46, v51
	v_xor_b32_e32 v46, v46, v50
	v_cndmask_b32_e32 v48, v63, v48, vcc
	v_cndmask_b32_e32 v46, v63, v46, vcc
	v_mul_f32_e32 v47, v56, v46
	v_fma_f32 v46, v56, v48, -1.0
	v_pk_mul_f32 v[50:51], v[32:33], v[46:47]
	v_lshl_add_u32 v115, v36, 2, s77
	v_add_f32_e32 v48, v50, v51
	v_mov_b32_e32 v50, v47
	v_mov_b32_e32 v51, v32
	v_pk_mul_f32 v[50:51], v[32:33], v[50:51] op_sel_hi:[0,1]
	v_mov_b32_e32 v32, v33
	v_mov_b32_e32 v47, v33
	v_pk_mul_f32 v[32:33], v[32:33], v[46:47] op_sel_hi:[0,1]
	v_add_f32_e32 v33, v51, v33
	v_div_scale_f32 v46, s[6:7], v33, v33, v48
	v_rcp_f32_e32 v47, v46
	v_sub_f32_e32 v32, v50, v32
	v_mov_b32_e32 v111, v110
	v_fma_f32 v51, -v46, v47, 1.0
	v_fmac_f32_e32 v47, v51, v47
	v_div_scale_f32 v51, vcc, v48, v33, v48
	v_mul_f32_e32 v52, v51, v47
	v_fma_f32 v56, -v46, v52, v51
	v_fmac_f32_e32 v52, v56, v47
	v_fma_f32 v46, -v46, v52, v51
	v_div_fmas_f32 v46, v46, v47, v52
	v_div_scale_f32 v47, s[6:7], v33, v33, v32
	v_div_fixup_f32 v46, v46, v33, v48
	v_rcp_f32_e32 v48, v47
	s_nop 0
	v_fma_f32 v50, -v47, v48, 1.0
	v_fmac_f32_e32 v48, v50, v48
	v_div_scale_f32 v50, vcc, v32, v33, v32
	v_mul_f32_e32 v51, v50, v48
	v_fma_f32 v52, -v47, v51, v50
	v_fmac_f32_e32 v51, v52, v48
	v_fma_f32 v47, -v47, v51, v50
	v_div_fmas_f32 v47, v47, v48, v51
	v_div_fixup_f32 v32, v47, v33, v32
	v_pk_mul_f32 v[50:51], v[18:19], v[46:47] op_sel_hi:[1,0]
	v_pk_mul_f32 v[18:19], v[18:19], v[32:33] op_sel_hi:[1,0]
	v_pk_fma_f32 v[50:51], v[14:15], v[32:33], v[50:51] op_sel_hi:[1,0,1]
	v_pk_fma_f32 v[14:15], v[14:15], v[46:47], v[18:19] op_sel_hi:[1,0,1] neg_lo:[0,0,1] neg_hi:[0,0,1]
	v_pk_mul_f32 v[18:19], v[20:21], v[46:47] op_sel_hi:[1,0]
	v_pk_mul_f32 v[20:21], v[20:21], v[32:33] op_sel_hi:[1,0]
	v_pk_fma_f32 v[18:19], v[16:17], v[32:33], v[18:19] op_sel_hi:[1,0,1]
	v_pk_fma_f32 v[16:17], v[16:17], v[46:47], v[20:21] op_sel_hi:[1,0,1] neg_lo:[0,0,1] neg_hi:[0,0,1]
	v_pk_mul_f32 v[20:21], v[10:11], v[46:47] op_sel_hi:[1,0]
	v_pk_mul_f32 v[10:11], v[10:11], v[32:33] op_sel_hi:[1,0]
	v_pk_fma_f32 v[20:21], v[6:7], v[32:33], v[20:21] op_sel_hi:[1,0,1]
	v_pk_fma_f32 v[6:7], v[6:7], v[46:47], v[10:11] op_sel_hi:[1,0,1] neg_lo:[0,0,1] neg_hi:[0,0,1]
	v_pk_mul_f32 v[10:11], v[46:47], v[12:13] op_sel_hi:[0,1]
	v_cvt_pk_bf16_f32 v68, v6, v7
	v_mul_f32_e32 v6, v45, v45
	v_fmamk_f32 v7, v6, 0xb94c1982, v61
	v_fmaak_f32 v7, v6, v7, 0xbe2aaa9d
	v_mul_f32_e32 v7, v6, v7
	v_fmac_f32_e32 v45, v45, v7
	v_fmamk_f32 v7, v6, 0x37d75334, v62
	v_fmaak_f32 v7, v6, v7, 0x3d2aabf7
	v_fmaak_f32 v7, v6, v7, 0xbf000004
	v_pk_mul_f32 v[12:13], v[32:33], v[12:13] op_sel_hi:[0,1]
	v_fma_f32 v6, v6, v7, 1.0
	v_and_b32_e32 v7, 1, v44
	v_pk_fma_f32 v[10:11], v[32:33], v[8:9], v[10:11] op_sel_hi:[0,1,1]
	v_pk_fma_f32 v[8:9], v[46:47], v[8:9], v[12:13] op_sel_hi:[0,1,1] neg_lo:[0,0,1] neg_hi:[0,0,1]
	v_cmp_eq_u32_e64 s[6:7], 0, v7
	v_lshlrev_b32_e32 v7, 30, v44
	v_cvt_pk_bf16_f32 v69, v8, v9
	v_and_b32_e32 v7, 0x80000000, v7
	v_xor_b32_e32 v8, v41, v40
	v_cndmask_b32_e64 v6, v6, v45, s[6:7]
	v_xor_b32_e32 v7, v8, v7
	v_cmp_class_f32_e64 vcc, v40, s16
	v_xor_b32_e32 v6, v7, v6
	v_cvt_pk_bf16_f32 v73, v10, v11
	v_cndmask_b32_e32 v11, v63, v6, vcc
	v_mul_f32_e32 v6, v38, v39
	v_mul_f32_e32 v7, 0x3fb8aa3b, v6
	v_fma_f32 v8, v6, s17, -v7
	v_rndne_f32_e32 v9, v7
	v_fmac_f32_e32 v8, 0x32a5705f, v6
	v_sub_f32_e32 v7, v7, v9
	v_add_f32_e32 v7, v7, v8
	v_exp_f32_e32 v7, v7
	v_cvt_i32_f32_e32 v8, v9
	v_cmp_ngt_f32_e64 s[6:7], s18, v6
	v_cvt_pk_bf16_f32 v66, v14, v15
	v_xor_b32_e32 v12, v49, v31
	v_ldexp_f32 v7, v7, v8
	v_cndmask_b32_e64 v7, 0, v7, s[6:7]
	v_cmp_nlt_f32_e64 s[6:7], s19, v6
	v_mul_f32_e32 v6, v43, v43
	v_mul_f32_e32 v8, v54, v54
	v_cndmask_b32_e64 v14, v64, v7, s[6:7]
	v_fmamk_f32 v7, v6, 0xb94c1982, v61
	v_fmaak_f32 v7, v6, v7, 0xbe2aaa9d
	v_mul_f32_e32 v7, v6, v7
	v_fmac_f32_e32 v43, v43, v7
	v_fmamk_f32 v7, v6, 0x37d75334, v62
	v_fmamk_f32 v10, v8, 0xb94c1982, v61
	v_fmaak_f32 v7, v6, v7, 0x3d2aabf7
	v_fmaak_f32 v10, v8, v10, 0xbe2aaa9d
	v_fmaak_f32 v7, v6, v7, 0xbf000004
	v_mul_f32_e32 v10, v8, v10
	v_fma_f32 v6, v6, v7, 1.0
	v_and_b32_e32 v7, 1, v42
	v_fmac_f32_e32 v54, v54, v10
	v_fmamk_f32 v10, v8, 0x37d75334, v62
	v_cmp_eq_u32_e64 s[6:7], 0, v7
	v_fmaak_f32 v10, v8, v10, 0x3d2aabf7
	v_lshlrev_b32_e32 v7, 30, v42
	v_cndmask_b32_e64 v6, -v43, v6, s[6:7]
	v_fmaak_f32 v10, v8, v10, 0xbf000004
	v_bitop3_b32 v6, v7, v6, s11 bitop3:0x6c
	v_fma_f32 v8, v8, v10, 1.0
	v_and_b32_e32 v10, 1, v53
	v_cndmask_b32_e32 v6, v63, v6, vcc
	v_cmp_eq_u32_e32 vcc, 0, v10
	v_lshlrev_b32_e32 v10, 30, v53
	v_and_b32_e32 v10, 0x80000000, v10
	v_cndmask_b32_e32 v8, v8, v54, vcc
	v_xor_b32_e32 v10, v12, v10
	v_xor_b32_e32 v8, v10, v8
	v_cndmask_b32_e64 v8, v63, v8, s[4:5]
	v_mul_f32_e32 v13, v57, v8
	v_fma_f32 v12, v57, v55, -1.0
	v_cvt_pk_bf16_f32 v67, v16, v17
	v_pk_mul_f32 v[16:17], v[34:35], v[12:13]
	v_and_b32_e32 v9, 15, v36
	v_add_f32_e32 v10, v16, v17
	v_mov_b32_e32 v16, v13
	v_mov_b32_e32 v17, v34
	v_mov_b32_e32 v8, v35
	v_mov_b32_e32 v13, v35
	v_pk_mul_f32 v[16:17], v[34:35], v[16:17] op_sel_hi:[0,1]
	v_pk_mul_f32 v[12:13], v[8:9], v[12:13] op_sel_hi:[0,1]
	v_add_f32_e32 v13, v17, v13
	v_div_scale_f32 v8, s[4:5], v13, v13, v10
	v_rcp_f32_e32 v15, v8
	v_cvt_pk_bf16_f32 v71, v18, v19
	v_cvt_pk_bf16_f32 v72, v20, v21
	s_lshl_b64 s[6:7], s[14:15], 2
	v_fma_f32 v17, -v8, v15, 1.0
	v_fmac_f32_e32 v15, v17, v15
	v_div_scale_f32 v17, vcc, v10, v13, v10
	v_mul_f32_e32 v18, v17, v15
	v_fma_f32 v19, -v8, v18, v17
	v_fmac_f32_e32 v18, v19, v15
	v_fma_f32 v8, -v8, v18, v17
	v_div_fmas_f32 v8, v8, v15, v18
	v_div_fixup_f32 v8, v8, v13, v10
	v_sub_f32_e32 v10, v16, v12
	v_div_scale_f32 v12, s[4:5], v13, v13, v10
	v_rcp_f32_e32 v15, v12
	v_mul_f32_e32 v104, v14, v6
	v_lshl_add_u64 v[6:7], v[2:3], 0, s[6:7]
	v_lshl_add_u64 v[2:3], v[24:25], 0, s[8:9]
	v_fma_f32 v16, -v12, v15, 1.0
	v_fmac_f32_e32 v15, v16, v15
	v_div_scale_f32 v16, vcc, v10, v13, v10
	v_mul_f32_e32 v17, v16, v15
	v_fma_f32 v18, -v12, v17, v16
	v_fmac_f32_e32 v17, v18, v15
	v_fma_f32 v12, -v12, v17, v16
	v_div_fmas_f32 v12, v12, v15, v17
	v_div_fixup_f32 v10, v12, v13, v10
	v_or_b32_e32 v12, 0x200, v30
	v_mov_b32_e32 v13, s13
	v_lshlrev_b64 v[16:17], 2, v[12:13]
	v_lshl_add_u64 v[20:21], v[26:27], 0, v[16:17]
	v_lshl_add_u64 v[28:29], v[28:29], 0, v[16:17]
	global_load_dwordx4 v[16:19], v[20:21], off
	global_load_dwordx4 v[24:27], v[28:29], off
	v_lshl_or_b32 v12, v9, 6, s12
	v_lshlrev_b64 v[12:13], 2, v[12:13]
	v_lshl_add_u64 v[4:5], v[4:5], 0, s[6:7]
	v_lshl_add_u64 v[4:5], v[4:5], 0, v[12:13]
	s_lshl_b32 s4, s10, 4
	v_readlane_b32 s6, v254, 54
	v_readlane_b32 s7, v254, 55
	s_ashr_i32 s5, s4, 31
	v_mul_f32_e32 v106, v14, v11
	v_lshlrev_b32_e32 v14, 4, v36
	v_cvt_pk_bf16_f32 v70, v50, v51
	v_mov_b32_e32 v105, v104
	v_mov_b32_e32 v107, v106
	v_add_u32_e32 v119, s77, v14
	s_waitcnt vmcnt(0) lgkmcnt(0)
	v_pk_mul_f32 v[30:31], v[24:25], v[8:9] op_sel_hi:[1,0]
	v_pk_mul_f32 v[24:25], v[24:25], v[10:11] op_sel_hi:[1,0]
	v_pk_fma_f32 v[30:31], v[16:17], v[10:11], v[30:31] op_sel_hi:[1,0,1]
	v_pk_fma_f32 v[32:33], v[16:17], v[8:9], v[24:25] op_sel_hi:[1,0,1] neg_lo:[0,0,1] neg_hi:[0,0,1]
	v_pk_mul_f32 v[16:17], v[26:27], v[8:9] op_sel_hi:[1,0]
	v_cvt_pk_bf16_f32 v74, v32, v33
	v_pk_fma_f32 v[34:35], v[18:19], v[10:11], v[16:17] op_sel_hi:[1,0,1]
	v_pk_mul_f32 v[16:17], v[26:27], v[10:11] op_sel_hi:[1,0]
	v_cvt_pk_bf16_f32 v78, v30, v31
	v_pk_fma_f32 v[38:39], v[18:19], v[8:9], v[16:17] op_sel_hi:[1,0,1] neg_lo:[0,0,1] neg_hi:[0,0,1]
	global_load_dwordx4 v[16:19], v[20:21], off offset:16
	global_load_dwordx4 v[24:27], v[28:29], off offset:16
	v_cvt_pk_bf16_f32 v75, v38, v39
	v_cvt_pk_bf16_f32 v79, v34, v35
	s_waitcnt vmcnt(0) lgkmcnt(0)
	v_pk_mul_f32 v[20:21], v[24:25], v[8:9] op_sel_hi:[1,0]
	v_pk_mul_f32 v[24:25], v[24:25], v[10:11] op_sel_hi:[1,0]
	v_pk_fma_f32 v[20:21], v[16:17], v[10:11], v[20:21] op_sel_hi:[1,0,1]
	v_pk_fma_f32 v[16:17], v[16:17], v[8:9], v[24:25] op_sel_hi:[1,0,1] neg_lo:[0,0,1] neg_hi:[0,0,1]
	v_pk_mul_f32 v[24:25], v[8:9], v[26:27] op_sel_hi:[0,1]
	v_pk_mul_f32 v[26:27], v[10:11], v[26:27] op_sel_hi:[0,1]
	v_cvt_pk_bf16_f32 v76, v16, v17
	v_lshl_add_u64 v[16:17], v[6:7], 0, v[12:13]
	v_and_b32_e32 v6, -4, v37
	v_pk_fma_f32 v[24:25], v[10:11], v[18:19], v[24:25] op_sel_hi:[0,1,1]
	v_pk_fma_f32 v[18:19], v[8:9], v[18:19], v[26:27] op_sel_hi:[0,1,1] neg_lo:[0,0,1] neg_hi:[0,0,1]
	v_ashrrev_i32_e32 v7, 31, v6
	v_cvt_pk_bf16_f32 v77, v18, v19
	v_lshlrev_b64 v[18:19], 2, v[6:7]
	v_cvt_pk_bf16_f32 v80, v20, v21
	v_lshl_add_u64 v[20:21], v[16:17], 0, v[18:19]
	v_cvt_pk_bf16_f32 v81, v24, v25
	v_lshl_add_u64 v[4:5], v[4:5], 0, v[18:19]
	global_load_dwordx4 v[16:19], v[20:21], off
	global_load_dwordx4 v[24:27], v[4:5], off
	v_and_b32_e32 v8, 1, v36
	v_lshlrev_b32_e32 v15, 5, v6
	v_mov_b32_e32 v6, 0x60
	v_lshl_add_u32 v13, v9, 1, s77
	v_add_u32_e32 v117, v13, v15
	s_waitcnt vmcnt(0) lgkmcnt(0)
	v_xor_b32_e32 v7, 0x80000000, v24
	v_cvt_pk_bf16_f32 v82, v16, v7
	v_xor_b32_e32 v7, 0x80000000, v25
	v_cvt_pk_bf16_f32 v83, v17, v7
	v_xor_b32_e32 v7, 0x80000000, v26
	v_cvt_pk_bf16_f32 v84, v18, v7
	v_xor_b32_e32 v7, 0x80000000, v27
	v_cvt_pk_bf16_f32 v85, v19, v7
	global_load_dwordx4 v[16:19], v[20:21], off offset:64
	global_load_dwordx4 v[24:27], v[4:5], off offset:64
	s_waitcnt vmcnt(0) lgkmcnt(0)
	v_xor_b32_e32 v7, 0x80000000, v24
	v_cvt_pk_bf16_f32 v86, v16, v7
	v_xor_b32_e32 v7, 0x80000000, v25
	v_cvt_pk_bf16_f32 v87, v17, v7
	v_xor_b32_e32 v7, 0x80000000, v26
	v_cvt_pk_bf16_f32 v88, v18, v7
	v_xor_b32_e32 v7, 0x80000000, v27
	v_cvt_pk_bf16_f32 v89, v19, v7
	global_load_dwordx4 v[16:19], v[20:21], off offset:128
	global_load_dwordx4 v[24:27], v[4:5], off offset:128
	s_waitcnt vmcnt(0) lgkmcnt(0)
	v_xor_b32_e32 v7, 0x80000000, v24
	v_cvt_pk_bf16_f32 v90, v16, v7
	v_xor_b32_e32 v7, 0x80000000, v25
	v_cvt_pk_bf16_f32 v91, v17, v7
	v_xor_b32_e32 v7, 0x80000000, v26
	v_cvt_pk_bf16_f32 v92, v18, v7
	v_xor_b32_e32 v7, 0x80000000, v27
	v_cvt_pk_bf16_f32 v93, v19, v7
	global_load_dwordx4 v[16:19], v[20:21], off offset:192
	global_load_dwordx4 v[24:27], v[4:5], off offset:192
	v_lshlrev_b32_e32 v7, 1, v22
	s_waitcnt vmcnt(0) lgkmcnt(0)
	v_xor_b32_e32 v4, 0x80000000, v24
	v_cvt_pk_bf16_f32 v94, v16, v4
	v_xor_b32_e32 v4, 0x80000000, v25
	v_cvt_pk_bf16_f32 v95, v17, v4
	v_xor_b32_e32 v4, 0x80000000, v26
	v_cvt_pk_bf16_f32 v96, v18, v4
	v_xor_b32_e32 v4, 0x80000000, v27
	v_cvt_pk_bf16_f32 v97, v19, v4
	v_or_b32_e32 v4, s4, v9
	v_ashrrev_i32_e32 v5, 31, v4
	v_lshl_add_u64 v[2:3], v[4:5], 2, v[2:3]
	global_load_dword v114, v[2:3], off
	v_lshl_add_u64 v[2:3], v[154:155], 0, s[6:7]
	s_lshl_b64 s[4:5], s[4:5], 1
	v_mul_u32_u24_e32 v4, 0xa00, v0
	v_lshl_add_u64 v[2:3], v[2:3], 0, s[4:5]
	v_lshlrev_b32_e32 v4, 1, v4
	v_mov_b32_e32 v5, v1
	v_lshl_add_u64 v[2:3], v[2:3], 0, v[4:5]
	v_lshl_add_u64 v[108:109], v[22:23], 1, v[2:3]
	global_load_dwordx4 v[2:5], v[108:109], off offset:3840
	v_lshlrev_b32_e32 v0, 5, v0
	v_add3_u32 v0, s77, v0, v7
	v_and_b32_e32 v7, -16, v36
	v_add_u32_e32 v12, s77, v7
	v_ashrrev_i32_e32 v7, 1, v36
	v_mad_i64_i32 v[10:11], s[6:7], v7, s61, 0
	v_readlane_b32 s6, v254, 56
	v_readlane_b32 s7, v254, 57
	v_lshl_or_b32 v10, v8, 4, v10
	v_mul_u32_u24_e32 v16, 0x210, v9
	v_lshl_or_b32 v17, v37, 5, v6
	v_lshl_add_u64 v[6:7], v[102:103], 0, s[6:7]
	v_lshl_add_u64 v[8:9], v[10:11], 0, s[4:5]
	v_lshl_add_u64 v[112:113], v[6:7], 0, v[8:9]
	s_mov_b32 s4, 0x14000
	v_add_u32_e32 v116, v12, v16
	v_add_u32_e32 v118, v13, v17
	s_waitcnt vmcnt(0)
.LBB0_431:
	s_cmp_lg_u32 s4, 0xa00000
	s_cselect_b32 s74, s4, 0x9ec000
	s_waitcnt lgkmcnt(0)
	ds_write_b128 v0, v[2:5] offset:16896
	v_lshl_add_u64 v[6:7], s[74:75], 1, v[108:109]
	global_load_dwordx4 v[98:101], v[6:7], off offset:3840
	v_mfma_f32_32x32x16_bf16 v[50:65], v[2:5], v[66:69], 0
	v_mul_f32_e64 v122, v106, v110
	v_mul_f32_e64 v123, v107, v111
	s_add_i32 s4, s4, 0x14000
	v_fma_f32 v124, v104, v110, -v123
	v_fma_f32 v125, v105, v111, -v122
	v_pk_fma_f32 v[110:111], v[104:105], v[110:111], v[122:123] op_sel:[0,0,1] op_sel_hi:[1,1,0]
	s_mov_b64 s[6:7], 0x28000
	v_mov_b32_e32 v125, v111
	s_cmp_lg_u32 s4, 0xa14000
	v_mfma_f32_32x32x16_bf16 v[18:33], v[2:5], v[74:77], 0
	v_mfma_f32_32x32x16_bf16 v[34:49], v[2:5], v[70:73], 0
	s_nop 10
	v_permlane32_swap_b32_e32 v50, v18
	v_mov_b32_e32 v120, v50
	v_permlane32_swap_b32_e32 v51, v19
	v_permlane32_swap_b32_e32 v52, v20
	v_mfma_f32_32x32x16_bf16 v[2:17], v[2:5], v[78:81], 0
	v_permlane32_swap_b32_e32 v53, v21
	v_permlane32_swap_b32_e32 v54, v22
	v_permlane32_swap_b32_e32 v55, v23
	v_permlane32_swap_b32_e32 v56, v24
	s_nop 7
	v_permlane32_swap_b32_e32 v34, v2
	v_mov_b32_e32 v121, v34
	v_pk_add_f32 v[110:111], v[124:125], v[120:121]
	v_mov_b32_e32 v34, v51
	v_pk_mul_f32 v[50:51], v[106:107], v[110:111]
	v_permlane32_swap_b32_e32 v35, v3
	v_pk_fma_f32 v[120:121], v[104:105], v[110:111], v[50:51] op_sel:[0,0,1] op_sel_hi:[1,1,0] neg_lo:[0,0,1] neg_hi:[0,0,1]
	v_pk_fma_f32 v[50:51], v[104:105], v[110:111], v[50:51] op_sel:[0,0,1] op_sel_hi:[1,1,0]
	v_cvt_pk_bf16_f32 v122, v110, v111
	v_mov_b32_e32 v121, v51
	v_pk_add_f32 v[34:35], v[120:121], v[34:35]
	v_permlane32_swap_b32_e32 v36, v4
	v_pk_mul_f32 v[110:111], v[106:107], v[34:35]
	v_cvt_pk_bf16_f32 v50, v34, v35
	v_pk_fma_f32 v[120:121], v[104:105], v[34:35], v[110:111] op_sel:[0,0,1] op_sel_hi:[1,1,0] neg_lo:[0,0,1] neg_hi:[0,0,1]
	v_pk_fma_f32 v[34:35], v[104:105], v[34:35], v[110:111] op_sel:[0,0,1] op_sel_hi:[1,1,0]
	ds_write2_b32 v115, v122, v50 offset1:132
	v_mov_b32_e32 v50, v52
	v_mov_b32_e32 v51, v36
	v_mov_b32_e32 v121, v35
	v_pk_add_f32 v[34:35], v[120:121], v[50:51]
	v_mov_b32_e32 v36, v53
	v_pk_mul_f32 v[50:51], v[106:107], v[34:35]
	v_cvt_pk_bf16_f32 v110, v34, v35
	v_pk_fma_f32 v[52:53], v[104:105], v[34:35], v[50:51] op_sel:[0,0,1] op_sel_hi:[1,1,0] neg_lo:[0,0,1] neg_hi:[0,0,1]
	v_pk_fma_f32 v[34:35], v[104:105], v[34:35], v[50:51] op_sel:[0,0,1] op_sel_hi:[1,1,0]
	v_permlane32_swap_b32_e32 v37, v5
	v_mov_b32_e32 v53, v35
	v_pk_add_f32 v[34:35], v[52:53], v[36:37]
	v_add_u32_e32 v37, 0x400, v115
	v_pk_mul_f32 v[50:51], v[106:107], v[34:35]
	v_cvt_pk_bf16_f32 v36, v34, v35
	v_pk_fma_f32 v[52:53], v[104:105], v[34:35], v[50:51] op_sel:[0,0,1] op_sel_hi:[1,1,0] neg_lo:[0,0,1] neg_hi:[0,0,1]
	v_pk_fma_f32 v[34:35], v[104:105], v[34:35], v[50:51] op_sel:[0,0,1] op_sel_hi:[1,1,0]
	ds_write2_b32 v37, v110, v36 offset0:8 offset1:140
	v_mov_b32_e32 v36, v18
	v_mov_b32_e32 v37, v2
	v_mov_b32_e32 v53, v35
	v_pk_add_f32 v[34:35], v[52:53], v[36:37]
	v_mov_b32_e32 v2, v19
	v_pk_mul_f32 v[18:19], v[106:107], v[34:35]
	v_cvt_pk_bf16_f32 v50, v34, v35
	v_pk_fma_f32 v[36:37], v[104:105], v[34:35], v[18:19] op_sel:[0,0,1] op_sel_hi:[1,1,0] neg_lo:[0,0,1] neg_hi:[0,0,1]
	v_pk_fma_f32 v[18:19], v[104:105], v[34:35], v[18:19] op_sel:[0,0,1] op_sel_hi:[1,1,0]
	v_permlane32_swap_b32_e32 v38, v6
	v_mov_b32_e32 v37, v19
	v_pk_add_f32 v[2:3], v[36:37], v[2:3]
	v_add_u32_e32 v19, 0x800, v115
	v_pk_mul_f32 v[34:35], v[106:107], v[2:3]
	v_cvt_pk_bf16_f32 v18, v2, v3
	v_pk_fma_f32 v[36:37], v[104:105], v[2:3], v[34:35] op_sel:[0,0,1] op_sel_hi:[1,1,0] neg_lo:[0,0,1] neg_hi:[0,0,1]
	v_pk_fma_f32 v[2:3], v[104:105], v[2:3], v[34:35] op_sel:[0,0,1] op_sel_hi:[1,1,0]
	ds_write2_b32 v19, v50, v18 offset0:16 offset1:148
	v_mov_b32_e32 v18, v20
	v_mov_b32_e32 v19, v4
	v_mov_b32_e32 v37, v3
	v_pk_add_f32 v[2:3], v[36:37], v[18:19]
	v_mov_b32_e32 v4, v21
	v_pk_mul_f32 v[18:19], v[106:107], v[2:3]
	v_cvt_pk_bf16_f32 v34, v2, v3
	v_pk_fma_f32 v[20:21], v[104:105], v[2:3], v[18:19] op_sel:[0,0,1] op_sel_hi:[1,1,0] neg_lo:[0,0,1] neg_hi:[0,0,1]
	v_pk_fma_f32 v[2:3], v[104:105], v[2:3], v[18:19] op_sel:[0,0,1] op_sel_hi:[1,1,0]
	v_permlane32_swap_b32_e32 v39, v7
	v_mov_b32_e32 v21, v3
	v_pk_add_f32 v[2:3], v[20:21], v[4:5]
	v_add_u32_e32 v5, 0xc00, v115
	v_pk_mul_f32 v[18:19], v[106:107], v[2:3]
	v_cvt_pk_bf16_f32 v4, v2, v3
	v_pk_fma_f32 v[20:21], v[104:105], v[2:3], v[18:19] op_sel:[0,0,1] op_sel_hi:[1,1,0] neg_lo:[0,0,1] neg_hi:[0,0,1]
	v_pk_fma_f32 v[2:3], v[104:105], v[2:3], v[18:19] op_sel:[0,0,1] op_sel_hi:[1,1,0]
	ds_write2_b32 v5, v34, v4 offset0:24 offset1:156
	v_mov_b32_e32 v4, v54
	v_mov_b32_e32 v5, v38
	v_mov_b32_e32 v21, v3
	v_pk_add_f32 v[2:3], v[20:21], v[4:5]
	v_mov_b32_e32 v38, v55
	v_pk_mul_f32 v[4:5], v[106:107], v[2:3]
	v_cvt_pk_bf16_f32 v20, v2, v3
	v_pk_fma_f32 v[18:19], v[104:105], v[2:3], v[4:5] op_sel:[0,0,1] op_sel_hi:[1,1,0] neg_lo:[0,0,1] neg_hi:[0,0,1]
	v_pk_fma_f32 v[2:3], v[104:105], v[2:3], v[4:5] op_sel:[0,0,1] op_sel_hi:[1,1,0]
	v_add_u32_e32 v5, 0x1000, v115
	v_mov_b32_e32 v19, v3
	v_pk_add_f32 v[2:3], v[18:19], v[38:39]
	v_permlane32_swap_b32_e32 v40, v8
	v_cvt_pk_bf16_f32 v4, v2, v3
	v_pk_mul_f32 v[18:19], v[106:107], v[2:3]
	ds_write2_b32 v5, v20, v4 offset0:32 offset1:164
	v_pk_fma_f32 v[20:21], v[104:105], v[2:3], v[18:19] op_sel:[0,0,1] op_sel_hi:[1,1,0] neg_lo:[0,0,1] neg_hi:[0,0,1]
	v_pk_fma_f32 v[2:3], v[104:105], v[2:3], v[18:19] op_sel:[0,0,1] op_sel_hi:[1,1,0]
	v_mov_b32_e32 v4, v56
	v_mov_b32_e32 v5, v40
	v_mov_b32_e32 v21, v3
	v_pk_add_f32 v[2:3], v[20:21], v[4:5]
	v_permlane32_swap_b32_e32 v57, v25
	v_pk_mul_f32 v[4:5], v[106:107], v[2:3]
	v_cvt_pk_bf16_f32 v20, v2, v3
	v_pk_fma_f32 v[18:19], v[104:105], v[2:3], v[4:5] op_sel:[0,0,1] op_sel_hi:[1,1,0] neg_lo:[0,0,1] neg_hi:[0,0,1]
	v_pk_fma_f32 v[2:3], v[104:105], v[2:3], v[4:5] op_sel:[0,0,1] op_sel_hi:[1,1,0]
	v_permlane32_swap_b32_e32 v41, v9
	v_mov_b32_e32 v40, v57
	v_mov_b32_e32 v19, v3
	v_pk_add_f32 v[2:3], v[18:19], v[40:41]
	v_add_u32_e32 v5, 0x1400, v115
	v_cvt_pk_bf16_f32 v4, v2, v3
	v_pk_mul_f32 v[18:19], v[106:107], v[2:3]
	ds_write2_b32 v5, v20, v4 offset0:40 offset1:172
	v_pk_fma_f32 v[20:21], v[104:105], v[2:3], v[18:19] op_sel:[0,0,1] op_sel_hi:[1,1,0] neg_lo:[0,0,1] neg_hi:[0,0,1]
	v_pk_fma_f32 v[2:3], v[104:105], v[2:3], v[18:19] op_sel:[0,0,1] op_sel_hi:[1,1,0]
	v_mov_b32_e32 v4, v22
	v_mov_b32_e32 v5, v6
	v_mov_b32_e32 v21, v3
	v_pk_add_f32 v[2:3], v[20:21], v[4:5]
	v_mov_b32_e32 v6, v23
	v_pk_mul_f32 v[4:5], v[106:107], v[2:3]
	v_cvt_pk_bf16_f32 v20, v2, v3
	v_pk_fma_f32 v[18:19], v[104:105], v[2:3], v[4:5] op_sel:[0,0,1] op_sel_hi:[1,1,0] neg_lo:[0,0,1] neg_hi:[0,0,1]
	v_pk_fma_f32 v[2:3], v[104:105], v[2:3], v[4:5] op_sel:[0,0,1] op_sel_hi:[1,1,0]
	v_add_u32_e32 v5, 0x1800, v115
	v_mov_b32_e32 v19, v3
	v_pk_add_f32 v[2:3], v[18:19], v[6:7]
	v_permlane32_swap_b32_e32 v58, v26
	v_pk_mul_f32 v[6:7], v[106:107], v[2:3]
	v_cvt_pk_bf16_f32 v4, v2, v3
	v_pk_fma_f32 v[18:19], v[104:105], v[2:3], v[6:7] op_sel:[0,0,1] op_sel_hi:[1,1,0] neg_lo:[0,0,1] neg_hi:[0,0,1]
	v_pk_fma_f32 v[2:3], v[104:105], v[2:3], v[6:7] op_sel:[0,0,1] op_sel_hi:[1,1,0]
	ds_write2_b32 v5, v20, v4 offset0:48 offset1:180
	v_mov_b32_e32 v4, v24
	v_mov_b32_e32 v5, v8
	v_mov_b32_e32 v19, v3
	v_pk_add_f32 v[2:3], v[18:19], v[4:5]
	v_mov_b32_e32 v8, v25
	v_pk_mul_f32 v[4:5], v[106:107], v[2:3]
	v_cvt_pk_bf16_f32 v18, v2, v3
	v_pk_fma_f32 v[6:7], v[104:105], v[2:3], v[4:5] op_sel:[0,0,1] op_sel_hi:[1,1,0] neg_lo:[0,0,1] neg_hi:[0,0,1]
	v_pk_fma_f32 v[2:3], v[104:105], v[2:3], v[4:5] op_sel:[0,0,1] op_sel_hi:[1,1,0]
	v_permlane32_swap_b32_e32 v42, v10
	v_mov_b32_e32 v7, v3
	v_pk_add_f32 v[2:3], v[6:7], v[8:9]
	v_add_u32_e32 v5, 0x1c00, v115
	v_pk_mul_f32 v[6:7], v[106:107], v[2:3]
	v_cvt_pk_bf16_f32 v4, v2, v3
	v_pk_fma_f32 v[8:9], v[104:105], v[2:3], v[6:7] op_sel:[0,0,1] op_sel_hi:[1,1,0] neg_lo:[0,0,1] neg_hi:[0,0,1]
	v_pk_fma_f32 v[2:3], v[104:105], v[2:3], v[6:7] op_sel:[0,0,1] op_sel_hi:[1,1,0]
	ds_write2_b32 v5, v18, v4 offset0:56 offset1:188
	v_mov_b32_e32 v4, v58
	v_mov_b32_e32 v5, v42
	v_mov_b32_e32 v9, v3
	v_pk_add_f32 v[2:3], v[8:9], v[4:5]
	v_permlane32_swap_b32_e32 v59, v27
	v_pk_mul_f32 v[4:5], v[106:107], v[2:3]
	v_cvt_pk_bf16_f32 v8, v2, v3
	v_pk_fma_f32 v[6:7], v[104:105], v[2:3], v[4:5] op_sel:[0,0,1] op_sel_hi:[1,1,0] neg_lo:[0,0,1] neg_hi:[0,0,1]
	v_pk_fma_f32 v[2:3], v[104:105], v[2:3], v[4:5] op_sel:[0,0,1] op_sel_hi:[1,1,0]
	v_permlane32_swap_b32_e32 v43, v11
	v_mov_b32_e32 v42, v59
	v_mov_b32_e32 v7, v3
	v_pk_add_f32 v[2:3], v[6:7], v[42:43]
	v_add_u32_e32 v5, 0x2000, v115
	v_cvt_pk_bf16_f32 v4, v2, v3
	v_pk_mul_f32 v[6:7], v[106:107], v[2:3]
	v_permlane32_swap_b32_e32 v60, v28
	v_permlane32_swap_b32_e32 v44, v12
	ds_write2_b32 v5, v8, v4 offset0:64 offset1:196
	v_pk_fma_f32 v[8:9], v[104:105], v[2:3], v[6:7] op_sel:[0,0,1] op_sel_hi:[1,1,0] neg_lo:[0,0,1] neg_hi:[0,0,1]
	v_pk_fma_f32 v[2:3], v[104:105], v[2:3], v[6:7] op_sel:[0,0,1] op_sel_hi:[1,1,0]
	v_mov_b32_e32 v4, v60
	v_mov_b32_e32 v5, v44
	v_mov_b32_e32 v9, v3
	v_pk_add_f32 v[2:3], v[8:9], v[4:5]
	v_permlane32_swap_b32_e32 v61, v29
	v_pk_mul_f32 v[4:5], v[106:107], v[2:3]
	v_cvt_pk_bf16_f32 v8, v2, v3
	v_pk_fma_f32 v[6:7], v[104:105], v[2:3], v[4:5] op_sel:[0,0,1] op_sel_hi:[1,1,0] neg_lo:[0,0,1] neg_hi:[0,0,1]
	v_pk_fma_f32 v[2:3], v[104:105], v[2:3], v[4:5] op_sel:[0,0,1] op_sel_hi:[1,1,0]
	v_permlane32_swap_b32_e32 v45, v13
	v_mov_b32_e32 v44, v61
	v_mov_b32_e32 v7, v3
	v_pk_add_f32 v[2:3], v[6:7], v[44:45]
	v_add_u32_e32 v5, 0x2400, v115
	v_cvt_pk_bf16_f32 v4, v2, v3
	v_pk_mul_f32 v[6:7], v[106:107], v[2:3]
	ds_write2_b32 v5, v8, v4 offset0:72 offset1:204
	v_pk_fma_f32 v[8:9], v[104:105], v[2:3], v[6:7] op_sel:[0,0,1] op_sel_hi:[1,1,0] neg_lo:[0,0,1] neg_hi:[0,0,1]
	v_pk_fma_f32 v[2:3], v[104:105], v[2:3], v[6:7] op_sel:[0,0,1] op_sel_hi:[1,1,0]
	v_mov_b32_e32 v4, v26
	v_mov_b32_e32 v5, v10
	v_mov_b32_e32 v9, v3
	v_pk_add_f32 v[2:3], v[8:9], v[4:5]
	v_mov_b32_e32 v10, v27
	v_pk_mul_f32 v[4:5], v[106:107], v[2:3]
	v_cvt_pk_bf16_f32 v8, v2, v3
	v_pk_fma_f32 v[6:7], v[104:105], v[2:3], v[4:5] op_sel:[0,0,1] op_sel_hi:[1,1,0] neg_lo:[0,0,1] neg_hi:[0,0,1]
	v_pk_fma_f32 v[2:3], v[104:105], v[2:3], v[4:5] op_sel:[0,0,1] op_sel_hi:[1,1,0]
	v_add_u32_e32 v5, 0x2800, v115
	v_mov_b32_e32 v7, v3
	v_pk_add_f32 v[2:3], v[6:7], v[10:11]
	v_permlane32_swap_b32_e32 v62, v30
	v_cvt_pk_bf16_f32 v4, v2, v3
	v_pk_mul_f32 v[6:7], v[106:107], v[2:3]
	ds_write2_b32 v5, v8, v4 offset0:80 offset1:212
	v_pk_fma_f32 v[8:9], v[104:105], v[2:3], v[6:7] op_sel:[0,0,1] op_sel_hi:[1,1,0] neg_lo:[0,0,1] neg_hi:[0,0,1]
	v_pk_fma_f32 v[2:3], v[104:105], v[2:3], v[6:7] op_sel:[0,0,1] op_sel_hi:[1,1,0]
	v_mov_b32_e32 v4, v28
	v_mov_b32_e32 v5, v12
	v_mov_b32_e32 v9, v3
	v_pk_add_f32 v[2:3], v[8:9], v[4:5]
	v_mov_b32_e32 v12, v29
	v_pk_mul_f32 v[4:5], v[106:107], v[2:3]
	v_cvt_pk_bf16_f32 v8, v2, v3
	v_pk_fma_f32 v[6:7], v[104:105], v[2:3], v[4:5] op_sel:[0,0,1] op_sel_hi:[1,1,0] neg_lo:[0,0,1] neg_hi:[0,0,1]
	v_pk_fma_f32 v[2:3], v[104:105], v[2:3], v[4:5] op_sel:[0,0,1] op_sel_hi:[1,1,0]
	v_add_u32_e32 v5, 0x2c00, v115
	v_mov_b32_e32 v7, v3
	v_pk_add_f32 v[2:3], v[6:7], v[12:13]
	v_permlane32_swap_b32_e32 v46, v14
	v_cvt_pk_bf16_f32 v4, v2, v3
	v_pk_mul_f32 v[6:7], v[106:107], v[2:3]
	ds_write2_b32 v5, v8, v4 offset0:88 offset1:220
	v_pk_fma_f32 v[8:9], v[104:105], v[2:3], v[6:7] op_sel:[0,0,1] op_sel_hi:[1,1,0] neg_lo:[0,0,1] neg_hi:[0,0,1]
	v_pk_fma_f32 v[2:3], v[104:105], v[2:3], v[6:7] op_sel:[0,0,1] op_sel_hi:[1,1,0]
	v_mov_b32_e32 v4, v62
	v_mov_b32_e32 v5, v46
	v_mov_b32_e32 v9, v3
	v_pk_add_f32 v[2:3], v[8:9], v[4:5]
	v_permlane32_swap_b32_e32 v63, v31
	v_pk_mul_f32 v[4:5], v[106:107], v[2:3]
	v_cvt_pk_bf16_f32 v8, v2, v3
	v_pk_fma_f32 v[6:7], v[104:105], v[2:3], v[4:5] op_sel:[0,0,1] op_sel_hi:[1,1,0] neg_lo:[0,0,1] neg_hi:[0,0,1]
	v_pk_fma_f32 v[2:3], v[104:105], v[2:3], v[4:5] op_sel:[0,0,1] op_sel_hi:[1,1,0]
	v_permlane32_swap_b32_e32 v47, v15
	v_mov_b32_e32 v46, v63
	v_mov_b32_e32 v7, v3
	v_pk_add_f32 v[2:3], v[6:7], v[46:47]
	v_add_u32_e32 v5, 0x3000, v115
	v_cvt_pk_bf16_f32 v4, v2, v3
	v_pk_mul_f32 v[6:7], v[106:107], v[2:3]
	v_permlane32_swap_b32_e32 v64, v32
	v_permlane32_swap_b32_e32 v48, v16
	ds_write2_b32 v5, v8, v4 offset0:96 offset1:228
	v_pk_fma_f32 v[8:9], v[104:105], v[2:3], v[6:7] op_sel:[0,0,1] op_sel_hi:[1,1,0] neg_lo:[0,0,1] neg_hi:[0,0,1]
	v_pk_fma_f32 v[2:3], v[104:105], v[2:3], v[6:7] op_sel:[0,0,1] op_sel_hi:[1,1,0]
	v_mov_b32_e32 v4, v64
	v_mov_b32_e32 v5, v48
	v_mov_b32_e32 v9, v3
	v_pk_add_f32 v[2:3], v[8:9], v[4:5]
	v_permlane32_swap_b32_e32 v65, v33
	v_pk_mul_f32 v[4:5], v[106:107], v[2:3]
	v_cvt_pk_bf16_f32 v8, v2, v3
	v_pk_fma_f32 v[6:7], v[104:105], v[2:3], v[4:5] op_sel:[0,0,1] op_sel_hi:[1,1,0] neg_lo:[0,0,1] neg_hi:[0,0,1]
	v_pk_fma_f32 v[2:3], v[104:105], v[2:3], v[4:5] op_sel:[0,0,1] op_sel_hi:[1,1,0]
	v_permlane32_swap_b32_e32 v49, v17
	v_mov_b32_e32 v48, v65
	v_mov_b32_e32 v7, v3
	v_pk_add_f32 v[2:3], v[6:7], v[48:49]
	v_add_u32_e32 v5, 0x3400, v115
	v_cvt_pk_bf16_f32 v4, v2, v3
	ds_write2_b32 v5, v8, v4 offset0:104 offset1:236
	v_pk_mul_f32 v[4:5], v[106:107], v[2:3]
	s_nop 0
	v_pk_fma_f32 v[6:7], v[104:105], v[2:3], v[4:5] op_sel:[0,0,1] op_sel_hi:[1,1,0] neg_lo:[0,0,1] neg_hi:[0,0,1]
	v_pk_fma_f32 v[2:3], v[104:105], v[2:3], v[4:5] op_sel:[0,0,1] op_sel_hi:[1,1,0]
	v_mov_b32_e32 v4, v32
	v_mov_b32_e32 v7, v3
	v_mov_b32_e32 v2, v30
	v_mov_b32_e32 v3, v14
	v_pk_add_f32 v[2:3], v[6:7], v[2:3]
	v_mov_b32_e32 v14, v31
	v_pk_mul_f32 v[6:7], v[106:107], v[2:3]
	v_cvt_pk_bf16_f32 v10, v2, v3
	v_pk_fma_f32 v[8:9], v[104:105], v[2:3], v[6:7] op_sel:[0,0,1] op_sel_hi:[1,1,0] neg_lo:[0,0,1] neg_hi:[0,0,1]
	v_pk_fma_f32 v[2:3], v[104:105], v[2:3], v[6:7] op_sel:[0,0,1] op_sel_hi:[1,1,0]
	v_add_u32_e32 v7, 0x3800, v115
	v_mov_b32_e32 v9, v3
	v_pk_add_f32 v[2:3], v[8:9], v[14:15]
	v_mov_b32_e32 v5, v16
	v_cvt_pk_bf16_f32 v6, v2, v3
	ds_write2_b32 v7, v10, v6 offset0:112 offset1:244
	v_pk_mul_f32 v[6:7], v[106:107], v[2:3]
	v_mov_b32_e32 v16, v33
	v_pk_fma_f32 v[8:9], v[104:105], v[2:3], v[6:7] op_sel:[0,0,1] op_sel_hi:[1,1,0] neg_lo:[0,0,1] neg_hi:[0,0,1]
	v_pk_fma_f32 v[2:3], v[104:105], v[2:3], v[6:7] op_sel:[0,0,1] op_sel_hi:[1,1,0]
	s_nop 0
	v_mov_b32_e32 v9, v3
	v_pk_add_f32 v[4:5], v[8:9], v[4:5]
	s_nop 0
	v_pk_mul_f32 v[6:7], v[106:107], v[4:5]
	v_cvt_pk_bf16_f32 v2, v4, v5
	v_pk_fma_f32 v[8:9], v[104:105], v[4:5], v[6:7] op_sel:[0,0,1] op_sel_hi:[1,1,0] neg_lo:[0,0,1] neg_hi:[0,0,1]
	v_pk_fma_f32 v[4:5], v[104:105], v[4:5], v[6:7] op_sel:[0,0,1] op_sel_hi:[1,1,0]
	s_nop 0
	v_mov_b32_e32 v9, v5
	v_pk_add_f32 v[110:111], v[8:9], v[16:17]
	v_add_u32_e32 v4, 0x3c00, v115
	v_cvt_pk_bf16_f32 v3, v110, v111
	ds_write2_b32 v4, v2, v3 offset0:120 offset1:252
	s_waitcnt lgkmcnt(0)
	ds_read_b128 v[2:5], v116
	ds_read_b128 v[6:9], v116 offset:64
	s_waitcnt lgkmcnt(0)
	v_mfma_f32_16x16x32_bf16 v[2:5], v[2:5], v[82:85], 0
	v_mfma_f32_16x16x32_bf16 v[2:5], v[6:9], v[86:89], v[2:5]
	ds_read_b128 v[6:9], v116 offset:128
	s_waitcnt lgkmcnt(0)
	v_mfma_f32_16x16x32_bf16 v[2:5], v[6:9], v[90:93], v[2:5]
	ds_read_b128 v[6:9], v116 offset:192
	s_waitcnt lgkmcnt(0)
	v_mfma_f32_16x16x32_bf16 v[2:5], v[6:9], v[94:97], v[2:5]
	ds_read_u16 v6, v117 offset:16896
	ds_read_u16 v7, v117 offset:16928
	s_waitcnt lgkmcnt(0)
	v_lshlrev_b32_e32 v6, 16, v6
	s_nop 3
	v_fma_f32 v2, v114, v6, v2
	v_mul_f32_e32 v6, 0x3d372713, v2
	v_mul_f32_e32 v6, v2, v6
	v_fma_f32 v6, v2, v6, v2
	v_mul_f32_e32 v6, 0x3f4c422a, v6
	v_add_f32_e32 v6, v6, v6
	v_mul_f32_e32 v6, 0x3fb8aa3b, v6
	v_exp_f32_e32 v6, v6
	v_mul_f32_e32 v2, 0.5, v2
	v_add_f32_e32 v6, 1.0, v6
	v_rcp_f32_e32 v6, v6
	s_nop 0
	v_fma_f32 v6, v6, -2.0, 1.0
	v_add_f32_e32 v6, 1.0, v6
	v_mul_f32_e32 v2, v2, v6
	v_cvt_pk_bf16_f32 v2, v2, s0
	ds_write_b16 v117, v2 offset:16896
	v_lshlrev_b32_e32 v2, 16, v7
	v_fma_f32 v2, v114, v2, v3
	v_mul_f32_e32 v3, 0x3d372713, v2
	v_mul_f32_e32 v3, v2, v3
	v_fma_f32 v3, v2, v3, v2
	v_mul_f32_e32 v3, 0x3f4c422a, v3
	v_add_f32_e32 v3, v3, v3
	v_mul_f32_e32 v3, 0x3fb8aa3b, v3
	v_exp_f32_e32 v3, v3
	v_mul_f32_e32 v2, 0.5, v2
	v_add_f32_e32 v3, 1.0, v3
	v_rcp_f32_e32 v3, v3
	s_nop 0
	v_fma_f32 v3, v3, -2.0, 1.0
	v_add_f32_e32 v3, 1.0, v3
	v_mul_f32_e32 v2, v2, v3
	v_cvt_pk_bf16_f32 v2, v2, s0
	ds_write_b16 v117, v2 offset:16928
	ds_read_u16 v2, v117 offset:16960
	s_waitcnt lgkmcnt(0)
	v_lshlrev_b32_e32 v2, 16, v2
	v_fma_f32 v2, v114, v2, v4
	v_mul_f32_e32 v3, 0x3d372713, v2
	v_mul_f32_e32 v3, v2, v3
	v_fma_f32 v3, v2, v3, v2
	v_mul_f32_e32 v3, 0x3f4c422a, v3
	v_add_f32_e32 v3, v3, v3
	v_mul_f32_e32 v3, 0x3fb8aa3b, v3
	v_exp_f32_e32 v3, v3
	v_mul_f32_e32 v2, 0.5, v2
	v_add_f32_e32 v3, 1.0, v3
	v_rcp_f32_e32 v3, v3
	s_nop 0
	v_fma_f32 v3, v3, -2.0, 1.0
	v_add_f32_e32 v3, 1.0, v3
	v_mul_f32_e32 v2, v2, v3
	v_cvt_pk_bf16_f32 v2, v2, s0
	ds_write_b16 v117, v2 offset:16960
	ds_read_u16 v2, v118 offset:16896
	s_waitcnt lgkmcnt(0)
	v_lshlrev_b32_e32 v2, 16, v2
	v_fmac_f32_e32 v5, v114, v2
	v_mul_f32_e32 v2, 0x3d372713, v5
	v_mul_f32_e32 v2, v5, v2
	v_fma_f32 v2, v5, v2, v5
	v_mul_f32_e32 v2, 0x3f4c422a, v2
	v_add_f32_e32 v2, v2, v2
	v_mul_f32_e32 v2, 0x3fb8aa3b, v2
	v_exp_f32_e32 v2, v2
	v_mul_f32_e32 v3, 0.5, v5
	v_add_f32_e32 v2, 1.0, v2
	v_rcp_f32_e32 v2, v2
	s_nop 0
	v_fma_f32 v2, v2, -2.0, 1.0
	v_add_f32_e32 v2, 1.0, v2
	v_mul_f32_e32 v2, v3, v2
	v_cvt_pk_bf16_f32 v2, v2, s0
	ds_write_b16 v118, v2 offset:16896
	ds_read_b128 v[2:5], v116 offset:8448
	ds_read_b128 v[6:9], v116 offset:8512
	s_waitcnt lgkmcnt(0)
	v_mfma_f32_16x16x32_bf16 v[2:5], v[2:5], v[82:85], 0
	v_mfma_f32_16x16x32_bf16 v[2:5], v[6:9], v[86:89], v[2:5]
	ds_read_b128 v[6:9], v116 offset:8576
	s_waitcnt lgkmcnt(0)
	v_mfma_f32_16x16x32_bf16 v[2:5], v[6:9], v[90:93], v[2:5]
	ds_read_b128 v[6:9], v116 offset:8640
	s_waitcnt lgkmcnt(0)
	v_mfma_f32_16x16x32_bf16 v[2:5], v[6:9], v[94:97], v[2:5]
	ds_read_u16 v6, v117 offset:17408
	ds_read_u16 v7, v117 offset:17440
	s_waitcnt lgkmcnt(0)
	v_lshlrev_b32_e32 v6, 16, v6
	s_nop 3
	v_fma_f32 v2, v114, v6, v2
	v_mul_f32_e32 v6, 0x3d372713, v2
	v_mul_f32_e32 v6, v2, v6
	v_fma_f32 v6, v2, v6, v2
	v_mul_f32_e32 v6, 0x3f4c422a, v6
	v_add_f32_e32 v6, v6, v6
	v_mul_f32_e32 v6, 0x3fb8aa3b, v6
	v_exp_f32_e32 v6, v6
	v_mul_f32_e32 v2, 0.5, v2
	v_add_f32_e32 v6, 1.0, v6
	v_rcp_f32_e32 v6, v6
	s_nop 0
	v_fma_f32 v6, v6, -2.0, 1.0
	v_add_f32_e32 v6, 1.0, v6
	v_mul_f32_e32 v2, v2, v6
	v_cvt_pk_bf16_f32 v2, v2, s0
	ds_write_b16 v117, v2 offset:17408
	v_lshlrev_b32_e32 v2, 16, v7
	v_fma_f32 v2, v114, v2, v3
	v_mul_f32_e32 v3, 0x3d372713, v2
	v_mul_f32_e32 v3, v2, v3
	v_fma_f32 v3, v2, v3, v2
	v_mul_f32_e32 v3, 0x3f4c422a, v3
	v_add_f32_e32 v3, v3, v3
	v_mul_f32_e32 v3, 0x3fb8aa3b, v3
	v_exp_f32_e32 v3, v3
	v_mul_f32_e32 v2, 0.5, v2
	v_add_f32_e32 v3, 1.0, v3
	v_rcp_f32_e32 v3, v3
	s_nop 0
	v_fma_f32 v3, v3, -2.0, 1.0
	v_add_f32_e32 v3, 1.0, v3
	v_mul_f32_e32 v2, v2, v3
	v_cvt_pk_bf16_f32 v2, v2, s0
	ds_write_b16 v117, v2 offset:17440
	ds_read_u16 v2, v117 offset:17472
	s_waitcnt lgkmcnt(0)
	v_lshlrev_b32_e32 v2, 16, v2
	v_fma_f32 v2, v114, v2, v4
	v_mul_f32_e32 v3, 0x3d372713, v2
	v_mul_f32_e32 v3, v2, v3
	v_fma_f32 v3, v2, v3, v2
	v_mul_f32_e32 v3, 0x3f4c422a, v3
	v_add_f32_e32 v3, v3, v3
	v_mul_f32_e32 v3, 0x3fb8aa3b, v3
	v_exp_f32_e32 v3, v3
	v_mul_f32_e32 v2, 0.5, v2
	v_add_f32_e32 v3, 1.0, v3
	v_rcp_f32_e32 v3, v3
	s_nop 0
	v_fma_f32 v3, v3, -2.0, 1.0
	v_add_f32_e32 v3, 1.0, v3
	v_mul_f32_e32 v2, v2, v3
	v_cvt_pk_bf16_f32 v2, v2, s0
	ds_write_b16 v117, v2 offset:17472
	ds_read_u16 v2, v117 offset:17504
	s_waitcnt lgkmcnt(0)
	v_lshlrev_b32_e32 v2, 16, v2
	v_fmac_f32_e32 v5, v114, v2
	v_mul_f32_e32 v2, 0x3d372713, v5
	v_mul_f32_e32 v2, v5, v2
	v_fma_f32 v2, v5, v2, v5
	v_mul_f32_e32 v2, 0x3f4c422a, v2
	v_add_f32_e32 v2, v2, v2
	v_mul_f32_e32 v2, 0x3fb8aa3b, v2
	v_exp_f32_e32 v2, v2
	v_mul_f32_e32 v3, 0.5, v5
	v_add_f32_e32 v2, 1.0, v2
	v_rcp_f32_e32 v2, v2
	s_nop 0
	v_fma_f32 v2, v2, -2.0, 1.0
	v_add_f32_e32 v2, 1.0, v2
	v_mul_f32_e32 v2, v3, v2
	v_cvt_pk_bf16_f32 v2, v2, s0
	ds_write_b16 v117, v2 offset:17504
	s_waitcnt lgkmcnt(0)
	ds_read_b128 v[2:5], v119 offset:16896
	s_waitcnt lgkmcnt(0)
	global_store_dwordx4 v[112:113], v[2:5], off
	s_waitcnt lgkmcnt(0)
	s_waitcnt vmcnt(1)
	s_nop 0
	v_mov_b64_e32 v[2:3], v[98:99]
	v_lshl_add_u64 v[112:113], v[112:113], 0, s[6:7]
	v_mov_b64_e32 v[4:5], v[100:101]
	s_cbranch_scc1 .LBB0_431

.LBB0_628:
	s_cmp_lt_i32 s4, 32
	s_cselect_b64 vcc, -1, 0
	s_waitcnt lgkmcnt(0)
	v_cndmask_b32_e32 v0, v147, v146, vcc
	s_lshl_b32 s4, 1, s4
	v_and_b32_e32 v0, s4, v0
	s_lshl_b32 s8, s8, 5
	v_cmp_ne_u32_e64 s[6:7], 0, v0
	v_cndmask_b32_e32 v0, v153, v152, vcc
	s_add_i32 s9, s9, s8
	v_and_b32_e32 v0, s4, v0
	s_or_b32 s8, s9, 31
	v_cmp_ne_u32_e64 s[4:5], 0, v0
	s_cmp_gt_i32 s8, s45
	s_mov_b64 s[56:57], 0
	s_cbranch_scc1 .LBB0_630
	s_mov_b64 s[56:57], -1

.LBB0_632:
	s_nop 7
	v_max_f32_e32 v0, v67, v67
	v_max_f32_e32 v196, v66, v66
	v_max_f32_e32 v0, v196, v0
	v_max3_f32 v0, v0, v68, v69
	v_max3_f32 v0, v0, v70, v71
	v_max3_f32 v0, v0, v72, v73
	v_max3_f32 v0, v0, v74, v75
	v_max3_f32 v0, v0, v76, v77
	v_max3_f32 v0, v0, v78, v79
	v_max3_f32 v0, v0, v80, v81
	v_cndmask_b32_e64 v0, v248, v0, s[6:7]
	v_mov_b32_e32 v196, v0
	s_nop 1
	v_permlane32_swap_b32_e32 v0, v196
	v_max_f32_e32 v196, v196, v196
	v_max_f32_e32 v0, v0, v0
	v_max_f32_e32 v0, v0, v196
	v_mul_f32_e32 v0, 0x3e38aa3b, v0
	v_max_f32_e32 v196, v203, v203
	v_max_f32_e32 v0, v196, v0
	v_sub_f32_e32 v196, v0, v203
	v_cmp_lt_f32_e32 vcc, s67, v196
	s_cbranch_vccz .LBB0_634
	v_sub_f32_e32 v196, v203, v0
	v_exp_f32_e32 v204, v196
	s_nop 0
	v_mul_f32_e32 v151, v151, v204
	v_pk_mul_f32 v[64:65], v[64:65], v[204:205] op_sel_hi:[1,0]
	v_pk_mul_f32 v[62:63], v[62:63], v[204:205] op_sel_hi:[1,0]
	v_pk_mul_f32 v[60:61], v[60:61], v[204:205] op_sel_hi:[1,0]
	v_pk_mul_f32 v[58:59], v[58:59], v[204:205] op_sel_hi:[1,0]
	v_pk_mul_f32 v[56:57], v[56:57], v[204:205] op_sel_hi:[1,0]
	v_pk_mul_f32 v[54:55], v[54:55], v[204:205] op_sel_hi:[1,0]
	v_pk_mul_f32 v[52:53], v[52:53], v[204:205] op_sel_hi:[1,0]
	v_pk_mul_f32 v[50:51], v[50:51], v[204:205] op_sel_hi:[1,0]
	v_pk_mul_f32 v[48:49], v[48:49], v[204:205] op_sel_hi:[1,0]
	v_pk_mul_f32 v[46:47], v[46:47], v[204:205] op_sel_hi:[1,0]
	v_pk_mul_f32 v[44:45], v[44:45], v[204:205] op_sel_hi:[1,0]
	v_pk_mul_f32 v[42:43], v[42:43], v[204:205] op_sel_hi:[1,0]
	v_pk_mul_f32 v[40:41], v[40:41], v[204:205] op_sel_hi:[1,0]
	v_pk_mul_f32 v[38:39], v[38:39], v[204:205] op_sel_hi:[1,0]
	v_pk_mul_f32 v[36:37], v[36:37], v[204:205] op_sel_hi:[1,0]
	v_pk_mul_f32 v[34:35], v[34:35], v[204:205] op_sel_hi:[1,0]
	s_branch .LBB0_635

.LBB0_635:
	v_cndmask_b32_e64 v222, -v248, v0, s[6:7]
	v_fma_f32 v66, v66, s66, -v222
	v_exp_f32_e32 v203, v66
	v_fma_f32 v66, v67, s66, -v222
	v_exp_f32_e32 v204, v66
	v_fma_f32 v66, v68, s66, -v222
	v_exp_f32_e32 v205, v66
	v_fma_f32 v66, v69, s66, -v222
	v_exp_f32_e32 v206, v66
	v_fma_f32 v66, v70, s66, -v222
	v_exp_f32_e32 v207, v66
	v_fma_f32 v66, v71, s66, -v222
	v_exp_f32_e32 v208, v66
	v_fma_f32 v66, v72, s66, -v222
	v_exp_f32_e32 v209, v66
	v_fma_f32 v66, v73, s66, -v222
	v_exp_f32_e32 v210, v66
	v_fma_f32 v66, v74, s66, -v222
	v_exp_f32_e32 v211, v66
	v_fma_f32 v66, v75, s66, -v222
	v_exp_f32_e32 v212, v66
	v_fma_f32 v66, v76, s66, -v222
	v_exp_f32_e32 v213, v66
	v_fma_f32 v66, v77, s66, -v222
	v_exp_f32_e32 v214, v66
	v_fma_f32 v66, v78, s66, -v222
	v_exp_f32_e32 v215, v66
	v_fma_f32 v66, v79, s66, -v222
	v_exp_f32_e32 v216, v66
	v_fma_f32 v66, v80, s66, -v222
	v_exp_f32_e32 v217, v66
	v_fma_f32 v66, v81, s66, -v222
	v_exp_f32_e32 v218, v66
	v_cvt_pk_bf16_f32 v66, v203, v204
	v_cvt_pk_bf16_f32 v67, v205, v206
	v_cvt_pk_bf16_f32 v68, v207, v208
	v_cvt_pk_bf16_f32 v69, v209, v210
	v_cvt_pk_bf16_f32 v70, v211, v212
	v_cvt_pk_bf16_f32 v71, v213, v214
	s_waitcnt vmcnt(0) lgkmcnt(0)
	v_mfma_f32_32x32x16_bf16 v[50:65], v[142:145], v[66:69], v[50:65]
	v_cvt_pk_bf16_f32 v72, v215, v216
	v_cvt_pk_bf16_f32 v73, v217, v218
	s_lshl_b32 s8, s90, 5
	s_add_i32 s8, s8, s91
	v_mad_u64_u32 v[220:221], s[8:9], s8, v247, v[180:181]
	s_xor_b64 s[6:7], s[56:57], -1
	v_mfma_f32_32x32x16_bf16 v[34:49], v[134:137], v[66:69], v[34:49]
	s_andn2_b64 vcc, exec, s[6:7]
	v_mfma_f32_32x32x16_bf16 v[50:65], v[138:141], v[70:73], v[50:65]
	v_mfma_f32_32x32x16_bf16 v[34:49], v[130:133], v[70:73], v[34:49]
	v_mfma_f32_32x32x16_bf16 v[66:81], v[118:121], v[98:101], 0
	v_mfma_f32_32x32x16_bf16 v[66:81], v[122:125], v[102:105], v[66:81]
	v_mfma_f32_32x32x16_bf16 v[66:81], v[126:129], v[106:109], v[66:81]
	v_mfma_f32_32x32x16_bf16 v[66:81], v[114:117], v[110:113], v[66:81]
	global_load_dwordx4 v[118:121], v[220:221], off offset:1536
	global_load_dwordx4 v[122:125], v[220:221], off offset:1568
	global_load_dwordx4 v[126:129], v[220:221], off offset:1600
	global_load_dwordx4 v[114:117], v[220:221], off offset:1632
	s_cbranch_vccnz .LBB0_637
	v_cmp_le_i32_e32 vcc, v186, v174
	s_and_b64 vcc, s[4:5], vcc
	s_nop 4
	v_cndmask_b32_e32 v66, v248, v66, vcc
	v_cmp_lt_i32_e32 vcc, v186, v174
	s_and_b64 vcc, s[4:5], vcc
	s_nop 0
	v_cndmask_b32_e32 v67, v248, v67, vcc
	v_cmp_le_i32_e32 vcc, v186, v175
	s_and_b64 vcc, s[4:5], vcc
	s_nop 0
	v_cndmask_b32_e32 v68, v248, v68, vcc
	v_cmp_le_i32_e32 vcc, v186, v184
	s_and_b64 vcc, s[4:5], vcc
	s_nop 0
	v_cndmask_b32_e32 v69, v248, v69, vcc
	v_cmp_le_i32_e32 vcc, v186, v172
	s_and_b64 vcc, s[4:5], vcc
	s_nop 0
	v_cndmask_b32_e32 v70, v248, v70, vcc
	v_cmp_lt_i32_e32 vcc, v186, v172
	s_and_b64 vcc, s[4:5], vcc
	s_nop 0
	v_cndmask_b32_e32 v71, v248, v71, vcc
	v_cmp_le_i32_e32 vcc, v202, v172
	s_and_b64 vcc, s[4:5], vcc
	s_nop 0
	v_cndmask_b32_e32 v72, v248, v72, vcc
	v_cmp_le_i32_e32 vcc, v200, v172
	s_and_b64 vcc, s[4:5], vcc
	s_nop 0
	v_cndmask_b32_e32 v73, v248, v73, vcc
	v_cmp_le_i32_e32 vcc, v192, v172
	s_and_b64 vcc, s[4:5], vcc
	s_nop 0
	v_cndmask_b32_e32 v74, v248, v74, vcc
	v_cmp_le_i32_e32 vcc, v201, v172
	s_and_b64 vcc, s[4:5], vcc
	s_nop 0
	v_cndmask_b32_e32 v75, v248, v75, vcc
	v_cmp_le_i32_e32 vcc, v193, v172
	s_and_b64 vcc, s[4:5], vcc
	s_nop 0
	v_cndmask_b32_e32 v76, v248, v76, vcc
	v_cmp_le_i32_e32 vcc, v191, v172
	s_and_b64 vcc, s[4:5], vcc
	s_nop 0
	v_cndmask_b32_e32 v77, v248, v77, vcc
	v_cmp_le_i32_e32 vcc, v190, v172
	s_and_b64 vcc, s[4:5], vcc
	s_nop 0
	v_cndmask_b32_e32 v78, v248, v78, vcc
	v_cmp_le_i32_e32 vcc, v189, v172
	s_and_b64 vcc, s[4:5], vcc
	s_nop 0
	v_cndmask_b32_e32 v79, v248, v79, vcc
	v_cmp_le_i32_e32 vcc, v188, v172
	s_and_b64 vcc, s[4:5], vcc
	s_nop 0
	v_cndmask_b32_e32 v80, v248, v80, vcc
	v_cmp_le_i32_e32 vcc, v187, v172
	s_and_b64 vcc, s[4:5], vcc
	s_nop 0
	v_cndmask_b32_e32 v81, v248, v81, vcc
.LBB0_637:
	s_nop 6
	v_max_f32_e32 v186, v67, v67
	v_max_f32_e32 v187, v66, v66
	v_max_f32_e32 v186, v187, v186
	v_max3_f32 v186, v186, v68, v69
	v_max3_f32 v186, v186, v70, v71
	v_max3_f32 v186, v186, v72, v73
	v_max3_f32 v186, v186, v74, v75
	v_max3_f32 v186, v186, v76, v77
	v_max3_f32 v186, v186, v78, v79
	v_max3_f32 v186, v186, v80, v81
	v_cndmask_b32_e64 v186, v248, v186, s[4:5]
	v_mov_b32_e32 v187, v186
	s_nop 1
	v_permlane32_swap_b32_e32 v186, v187
	v_max_f32_e32 v187, v187, v187
	v_max_f32_e32 v186, v186, v186
	v_max_f32_e32 v186, v186, v187
	v_mul_f32_e32 v186, 0x3e38aa3b, v186
	v_max_f32_e32 v187, v185, v185
	v_max_f32_e32 v186, v187, v186
	v_sub_f32_e32 v187, v186, v185
	v_cmp_lt_f32_e32 vcc, s67, v187
	s_cbranch_vccz .LBB0_639
	v_sub_f32_e32 v185, v185, v186
	v_exp_f32_e32 v188, v185
	s_nop 0
	v_mul_f32_e32 v150, v150, v188
	v_pk_mul_f32 v[32:33], v[32:33], v[188:189] op_sel_hi:[1,0]
	v_pk_mul_f32 v[30:31], v[30:31], v[188:189] op_sel_hi:[1,0]
	v_pk_mul_f32 v[28:29], v[28:29], v[188:189] op_sel_hi:[1,0]
	v_pk_mul_f32 v[26:27], v[26:27], v[188:189] op_sel_hi:[1,0]
	v_pk_mul_f32 v[24:25], v[24:25], v[188:189] op_sel_hi:[1,0]
	v_pk_mul_f32 v[22:23], v[22:23], v[188:189] op_sel_hi:[1,0]
	v_pk_mul_f32 v[20:21], v[20:21], v[188:189] op_sel_hi:[1,0]
	v_pk_mul_f32 v[18:19], v[18:19], v[188:189] op_sel_hi:[1,0]
	v_pk_mul_f32 v[16:17], v[16:17], v[188:189] op_sel_hi:[1,0]
	v_pk_mul_f32 v[14:15], v[14:15], v[188:189] op_sel_hi:[1,0]
	v_pk_mul_f32 v[12:13], v[12:13], v[188:189] op_sel_hi:[1,0]
	v_pk_mul_f32 v[10:11], v[10:11], v[188:189] op_sel_hi:[1,0]
	v_pk_mul_f32 v[8:9], v[8:9], v[188:189] op_sel_hi:[1,0]
	v_pk_mul_f32 v[6:7], v[6:7], v[188:189] op_sel_hi:[1,0]
	v_pk_mul_f32 v[4:5], v[4:5], v[188:189] op_sel_hi:[1,0]
	v_pk_mul_f32 v[2:3], v[2:3], v[188:189] op_sel_hi:[1,0]
	s_branch .LBB0_640

.LBB0_640:
	v_cndmask_b32_e64 v223, -v248, v186, s[4:5]
	v_add_f32_e32 v185, 0, v203
	v_add_f32_e32 v185, v204, v185
	v_add_f32_e32 v185, v205, v185
	v_add_f32_e32 v185, v206, v185
	v_add_f32_e32 v185, v207, v185
	v_add_f32_e32 v185, v208, v185
	v_add_f32_e32 v185, v209, v185
	v_add_f32_e32 v185, v210, v185
	v_add_f32_e32 v185, v211, v185
	v_add_f32_e32 v185, v212, v185
	v_add_f32_e32 v185, v213, v185
	v_add_f32_e32 v185, v214, v185
	v_fma_f32 v66, v66, s66, -v223
	v_add_f32_e32 v185, v215, v185
	v_exp_f32_e32 v66, v66
	v_fma_f32 v67, v67, s66, -v223
	v_add_f32_e32 v185, v216, v185
	v_exp_f32_e32 v67, v67
	v_fma_f32 v68, v68, s66, -v223
	v_add_f32_e32 v185, v217, v185
	v_exp_f32_e32 v68, v68
	v_fma_f32 v69, v69, s66, -v223
	v_fma_f32 v70, v70, s66, -v223
	v_fma_f32 v71, v71, s66, -v223
	v_fma_f32 v72, v72, s66, -v223
	v_fma_f32 v73, v73, s66, -v223
	v_add_f32_e32 v185, v218, v185
	v_exp_f32_e32 v69, v69
	v_exp_f32_e32 v70, v70
	v_exp_f32_e32 v71, v71
	v_exp_f32_e32 v72, v72
	v_exp_f32_e32 v73, v73
	v_add_f32_e32 v151, v151, v185
	v_add_f32_e32 v185, 0, v66
	v_add_f32_e32 v185, v67, v185
	v_add_f32_e32 v185, v68, v185
	v_add_f32_e32 v185, v69, v185
	v_cvt_pk_bf16_f32 v66, v66, v67
	v_cvt_pk_bf16_f32 v67, v68, v69
	v_cvt_pk_bf16_f32 v68, v70, v71
	v_cvt_pk_bf16_f32 v69, v72, v73
	v_fma_f32 v74, v74, s66, -v223
	v_fma_f32 v75, v75, s66, -v223
	v_mfma_f32_32x32x16_bf16 v[18:33], v[142:145], v[66:69], v[18:33]
	v_fma_f32 v76, v76, s66, -v223
	v_fma_f32 v77, v77, s66, -v223
	v_fma_f32 v78, v78, s66, -v223
	v_fma_f32 v79, v79, s66, -v223
	v_fma_f32 v80, v80, s66, -v223
	v_fma_f32 v81, v81, s66, -v223
	v_add_f32_e32 v185, v70, v185
	v_mfma_f32_32x32x16_bf16 v[2:17], v[134:137], v[66:69], v[2:17]
	v_exp_f32_e32 v74, v74
	v_exp_f32_e32 v75, v75
	v_exp_f32_e32 v76, v76
	v_exp_f32_e32 v77, v77
	v_exp_f32_e32 v78, v78
	v_exp_f32_e32 v79, v79
	v_exp_f32_e32 v80, v80
	v_exp_f32_e32 v81, v81
	v_add_f32_e32 v185, v71, v185
	v_add_f32_e32 v185, v72, v185
	v_add_f32_e32 v185, v73, v185
	v_add_f32_e32 v185, v74, v185
	v_cvt_pk_bf16_f32 v70, v74, v75
	v_cvt_pk_bf16_f32 v71, v76, v77
	v_cvt_pk_bf16_f32 v72, v78, v79
	v_cvt_pk_bf16_f32 v73, v80, v81
	v_add_f32_e32 v185, v75, v185
	v_add_f32_e32 v185, v76, v185
	v_mfma_f32_32x32x16_bf16 v[18:33], v[138:141], v[70:73], v[18:33]
	v_add_f32_e32 v185, v77, v185
	v_add_f32_e32 v185, v78, v185
	v_add_f32_e32 v185, v79, v185
	v_add_f32_e32 v185, v80, v185
	s_xor_b64 s[4:5], s[96:97], -1
	v_add_f32_e32 v185, v81, v185
	v_add_f32_e32 v150, v150, v185
	v_mfma_f32_32x32x16_bf16 v[2:17], v[130:133], v[70:73], v[2:17]
	s_and_b64 vcc, exec, s[4:5]
	s_cbranch_vccnz .LBB0_642
	s_mov_b32 s8, s90
	s_mov_b32 s4, s83
	v_mov_b32_e32 v203, v0
	v_mov_b32_e32 v185, v186
	s_branch .LBB0_626

	.amdhsa_kernel _Z8mega_fwd4Args
		.amdhsa_group_segment_fixed_size 0
		.amdhsa_private_segment_fixed_size 0
		.amdhsa_kernarg_size 488
		.amdhsa_user_sgpr_count 2
		.amdhsa_user_sgpr_dispatch_ptr 0
		.amdhsa_user_sgpr_queue_ptr 0
		.amdhsa_user_sgpr_kernarg_segment_ptr 1
		.amdhsa_user_sgpr_dispatch_id 0
		.amdhsa_user_sgpr_kernarg_preload_length 0
		.amdhsa_user_sgpr_kernarg_preload_offset 0
		.amdhsa_user_sgpr_private_segment_size 0
		.amdhsa_uses_dynamic_stack 0
		.amdhsa_enable_private_segment 0
		.amdhsa_system_sgpr_workgroup_id_x 1
		.amdhsa_system_sgpr_workgroup_id_y 0
		.amdhsa_system_sgpr_workgroup_id_z 0
		.amdhsa_system_sgpr_workgroup_info 0
		.amdhsa_system_vgpr_workitem_id 2
		.amdhsa_next_free_vgpr 256
		.amdhsa_next_free_sgpr 102
		.amdhsa_accum_offset 256
		.amdhsa_reserve_vcc 1
		.amdhsa_float_round_mode_32 0
		.amdhsa_float_round_mode_16_64 0
		.amdhsa_float_denorm_mode_32 3
		.amdhsa_float_denorm_mode_16_64 3
		.amdhsa_dx10_clamp 1
		.amdhsa_ieee_mode 1
		.amdhsa_fp16_overflow 0
		.amdhsa_tg_split 0
		.amdhsa_exception_fp_ieee_invalid_op 0
		.amdhsa_exception_fp_denorm_src 0
		.amdhsa_exception_fp_ieee_div_zero 0
		.amdhsa_exception_fp_ieee_overflow 0
		.amdhsa_exception_fp_ieee_underflow 0
		.amdhsa_exception_fp_ieee_inexact 0
		.amdhsa_exception_int_div_zero 0
	.end_amdhsa_kernel

amdhsa.kernels:
  - .agpr_count:     0
    .args:
      - .offset:         0
        .size:           232
        .value_kind:     by_value
      - .offset:         232
        .size:           4
        .value_kind:     hidden_block_count_x
      - .offset:         236
        .size:           4
        .value_kind:     hidden_block_count_y
      - .offset:         240
        .size:           4
        .value_kind:     hidden_block_count_z
      - .offset:         244
        .size:           2
        .value_kind:     hidden_group_size_x
      - .offset:         246
        .size:           2
        .value_kind:     hidden_group_size_y
      - .offset:         248
        .size:           2
        .value_kind:     hidden_group_size_z
      - .offset:         250
        .size:           2
        .value_kind:     hidden_remainder_x
      - .offset:         252
        .size:           2
        .value_kind:     hidden_remainder_y
      - .offset:         254
        .size:           2
        .value_kind:     hidden_remainder_z
      - .offset:         272
        .size:           8
        .value_kind:     hidden_global_offset_x
      - .offset:         280
        .size:           8
        .value_kind:     hidden_global_offset_y
      - .offset:         288
        .size:           8
        .value_kind:     hidden_global_offset_z
      - .offset:         296
        .size:           2
        .value_kind:     hidden_grid_dims
      - .offset:         320
        .size:           8
        .value_kind:     hidden_multigrid_sync_arg
      - .offset:         352
        .size:           4
        .value_kind:     hidden_dynamic_lds_size
    .group_segment_fixed_size: 0
    .kernarg_segment_align: 8
    .kernarg_segment_size: 488
    .language:       OpenCL C
    .language_version:
      - 2
      - 0
    .max_flat_workgroup_size: 512
    .name:           _Z8mega_fwd4Args
    .private_segment_fixed_size: 0
    .sgpr_count:     108
    .sgpr_spill_count: 85
    .symbol:         _Z8mega_fwd4Args.kd
    .uniform_work_group_size: 1
    .uses_dynamic_stack: false
    .vgpr_count:     256
    .vgpr_spill_count: 0
    .wavefront_size: 64
